# v6: + online-softmax fold in mixer B unmasked tile steps (max on raw scores, one fused scale-subtract op per element)
# baseline (speedup 1.0000x reference)
.LBB0_587:
	s_lshl_b64 s[6:7], 1, s22
	s_and_b64 s[8:9], s[6:7], s[38:39]
	s_cmp_eq_u64 s[8:9], 0
	s_cbranch_scc1 .LBB0_597
	s_add_i32 s8, 0, 0x4000
	s_cmp_eq_u32 s45, 0
	s_cselect_b32 s8, s8, s91
	v_add3_u32 v64, s8, v148, v150
	ds_read_b128 v[24:27], v64
	ds_read_b128 v[28:31], v64 offset:64
	ds_read_b128 v[32:35], v64 offset:2560
	ds_read_b128 v[36:39], v64 offset:2624
	s_cselect_b32 s8, s77, s46
	s_cmp_eq_u32 s22, 0
	s_waitcnt lgkmcnt(0)
	v_mfma_f32_16x16x32_bf16 v[24:27], v[24:27], v[20:23], 0
	v_mfma_f32_16x16x32_bf16 v[32:35], v[32:35], v[20:23], 0
	v_mfma_f32_16x16x32_bf16 v[108:111], v[28:31], v[0:3], v[24:27]
	s_nop 5
	ds_read_b128 v[24:27], v64 offset:5120
	ds_read_b128 v[28:31], v64 offset:5184
	v_mfma_f32_16x16x32_bf16 v[104:107], v[36:39], v[0:3], v[32:35]
	s_nop 2
	ds_read_b128 v[32:35], v64 offset:7680
	ds_read_b128 v[36:39], v64 offset:7744
	v_add3_u32 v64, s8, v149, v148
	ds_read_b128 v[92:95], v64
	ds_read_b128 v[88:91], v64 offset:64
	s_waitcnt lgkmcnt(0)
	v_mfma_f32_16x16x32_bf16 v[24:27], v[24:27], v[20:23], 0
	ds_read_b128 v[84:87], v64 offset:2560
	ds_read_b128 v[80:83], v64 offset:2624
	ds_read_b128 v[76:79], v64 offset:5120
	ds_read_b128 v[72:75], v64 offset:5184
	ds_read_b128 v[68:71], v64 offset:7680
	ds_read_b128 v[64:67], v64 offset:7744
	s_cselect_b64 s[8:9], -1, 0
	v_mfma_f32_16x16x32_bf16 v[100:103], v[28:31], v[0:3], v[24:27]
	s_and_b64 vcc, exec, s[8:9]
	v_mfma_f32_16x16x32_bf16 v[24:27], v[32:35], v[20:23], 0
	v_mfma_f32_16x16x32_bf16 v[96:99], v[36:39], v[0:3], v[24:27]
	s_cbranch_vccnz .LBB0_591
	s_lshl_b32 s8, s22, 6
	s_or_b32 s8, s8, 63
	s_cmp_le_i32 s8, s56
	s_mov_b64 s[8:9], -1
	s_cbranch_scc0 .LBB0_592
	s_nop 0
	v_and_b32_e32 v25, s7, v115
	v_and_b32_e32 v24, s6, v134
	v_cmp_eq_u64_e32 vcc, 0, v[24:25]
	s_mov_b64 s[8:9], 0
	s_nop 0
	v_cndmask_b32_e32 v24, 0, v241, vcc
	v_max3_f32 v27, v108, v109, v110
	v_max3_f32 v27, v27, v111, v104
	v_max3_f32 v27, v27, v105, v106
	v_max3_f32 v27, v27, v107, v100
	v_max3_f32 v27, v27, v101, v102
	v_max3_f32 v27, v27, v103, v96
	v_max3_f32 v27, v27, v97, v98
	v_max_f32_e32 v27, v27, v99
	v_mov_b32_e32 v127, v27
	s_nop 1
	v_permlane16_swap_b32_e32 v27, v127
	v_max_f32_e32 v27, v27, v127
	v_mov_b32_e32 v127, v27
	s_nop 1
	v_permlane32_swap_b32_e32 v27, v127
	v_max_f32_e32 v27, v27, v127
	v_fmamk_f32 v27, v27, 0x3e38aa3b, v24
	v_max3_f32 v127, v125, v27, s71
	v_sub_f32_e32 v27, v125, v127
	v_sub_f32_e32 v24, v24, v127
	v_exp_f32_e32 v142, v27
	v_fmamk_f32 v25, v108, 0x3e38aa3b, v24
	v_exp_f32_e32 v25, v25
	v_fmamk_f32 v26, v109, 0x3e38aa3b, v24
	v_exp_f32_e32 v26, v26
	v_fmamk_f32 v28, v110, 0x3e38aa3b, v24
	v_exp_f32_e32 v28, v28
	v_add_f32_e32 v138, 0, v25
	v_fmamk_f32 v29, v111, 0x3e38aa3b, v24
	v_exp_f32_e32 v29, v29
	v_add_f32_e32 v138, v26, v138
	v_fmamk_f32 v30, v104, 0x3e38aa3b, v24
	v_exp_f32_e32 v30, v30
	v_add_f32_e32 v138, v28, v138
	v_fmamk_f32 v31, v105, 0x3e38aa3b, v24
	v_exp_f32_e32 v31, v31
	v_add_f32_e32 v138, v29, v138
	v_fmamk_f32 v32, v106, 0x3e38aa3b, v24
	v_exp_f32_e32 v32, v32
	v_add_f32_e32 v138, v30, v138
	v_fmamk_f32 v33, v107, 0x3e38aa3b, v24
	v_exp_f32_e32 v33, v33
	v_add_f32_e32 v138, v31, v138
	v_fmamk_f32 v34, v100, 0x3e38aa3b, v24
	v_exp_f32_e32 v34, v34
	v_add_f32_e32 v138, v32, v138
	v_fmamk_f32 v35, v101, 0x3e38aa3b, v24
	v_exp_f32_e32 v35, v35
	v_add_f32_e32 v138, v33, v138
	v_fmamk_f32 v139, v102, 0x3e38aa3b, v24
	v_exp_f32_e32 v139, v139
	v_add_f32_e32 v138, v34, v138
	v_fmamk_f32 v140, v103, 0x3e38aa3b, v24
	v_exp_f32_e32 v140, v140
	v_add_f32_e32 v138, v35, v138
	v_fmamk_f32 v141, v96, 0x3e38aa3b, v24
	v_exp_f32_e32 v141, v141
	v_add_f32_e32 v36, v139, v138
	v_fmamk_f32 v143, v97, 0x3e38aa3b, v24
	v_exp_f32_e32 v143, v143
	v_add_f32_e32 v36, v140, v36
	v_fmamk_f32 v144, v98, 0x3e38aa3b, v24
	v_exp_f32_e32 v144, v144
	v_add_f32_e32 v36, v141, v36
	v_fmamk_f32 v24, v99, 0x3e38aa3b, v24
	v_exp_f32_e32 v24, v24
	v_add_f32_e32 v36, v143, v36
	v_add_f32_e32 v36, v144, v36
	v_add_f32_e32 v131, v24, v36
	v_fmac_f32_e32 v131, v121, v142
	v_cvt_pk_bf16_f32 v36, v25, v26
	v_cvt_pk_bf16_f32 v37, v28, v29
	v_cvt_pk_bf16_f32 v38, v30, v31
	v_cvt_pk_bf16_f32 v39, v32, v33
	v_cvt_pk_bf16_f32 v138, v34, v35
	v_cvt_pk_bf16_f32 v139, v139, v140
	v_cvt_pk_bf16_f32 v140, v141, v143
	v_cvt_pk_bf16_f32 v141, v144, v24
	v_pk_mul_f32 v[26:27], v[62:63], v[142:143] op_sel_hi:[1,0]
	v_pk_mul_f32 v[24:25], v[60:61], v[142:143] op_sel_hi:[1,0]
	v_pk_mul_f32 v[30:31], v[58:59], v[142:143] op_sel_hi:[1,0]
	v_pk_mul_f32 v[28:29], v[56:57], v[142:143] op_sel_hi:[1,0]
	v_pk_mul_f32 v[34:35], v[54:55], v[142:143] op_sel_hi:[1,0]
	v_pk_mul_f32 v[32:33], v[52:53], v[142:143] op_sel_hi:[1,0]
	v_pk_mul_f32 v[144:145], v[50:51], v[142:143] op_sel_hi:[1,0]
	v_pk_mul_f32 v[142:143], v[48:49], v[142:143] op_sel_hi:[1,0]
	s_waitcnt lgkmcnt(0)
	v_mfma_f32_16x16x32_bf16 v[24:27], v[92:95], v[36:39], v[24:27]
	v_mfma_f32_16x16x32_bf16 v[28:31], v[84:87], v[36:39], v[28:31]
	v_mfma_f32_16x16x32_bf16 v[32:35], v[76:79], v[36:39], v[32:35]
	v_mfma_f32_16x16x32_bf16 v[36:39], v[68:71], v[36:39], v[142:145]
	v_mfma_f32_16x16x32_bf16 v[24:27], v[88:91], v[138:141], v[24:27]
	v_mfma_f32_16x16x32_bf16 v[28:31], v[80:83], v[138:141], v[28:31]
	v_mfma_f32_16x16x32_bf16 v[32:35], v[72:75], v[138:141], v[32:35]
	v_mfma_f32_16x16x32_bf16 v[36:39], v[64:67], v[138:141], v[36:39]
	s_branch .LBB0_592

.LBB0_613:
	s_nop 2
	v_max3_f32 v82, v100, v101, v102
	v_max3_f32 v82, v82, v103, v96
	v_max3_f32 v82, v82, v97, v98
	v_max3_f32 v82, v82, v99, v88
	v_max3_f32 v82, v82, v89, v90
	v_max3_f32 v82, v82, v91, v84
	v_max3_f32 v82, v82, v85, v86
	v_max_f32_e32 v82, v82, v87
	v_mov_b32_e32 v131, v82
	s_nop 1
	v_permlane16_swap_b32_e32 v82, v131
	v_max_f32_e32 v82, v82, v131
	v_mov_b32_e32 v131, v82
	s_nop 1
	v_permlane32_swap_b32_e32 v82, v131
	v_max_f32_e32 v82, v82, v131
	v_mul_f32_e32 v82, s87, v82
	v_max3_f32 v131, v136, v82, s71
	v_sub_f32_e32 v82, v136, v131
	v_sub_f32_e32 v109, 0, v131
	v_exp_f32_e32 v156, v82
	v_fma_f32 v80, v100, s87, v109
	v_exp_f32_e32 v80, v80
	v_fma_f32 v81, v101, s87, v109
	v_exp_f32_e32 v81, v81
	v_fma_f32 v83, v102, s87, v109
	v_exp_f32_e32 v83, v83
	v_add_f32_e32 v152, 0, v80
	v_fma_f32 v92, v103, s87, v109
	v_exp_f32_e32 v92, v92
	v_add_f32_e32 v152, v81, v152
	v_fma_f32 v93, v96, s87, v109
	v_exp_f32_e32 v93, v93
	v_add_f32_e32 v152, v83, v152
	v_fma_f32 v94, v97, s87, v109
	v_exp_f32_e32 v94, v94
	v_add_f32_e32 v152, v92, v152
	v_fma_f32 v95, v98, s87, v109
	v_exp_f32_e32 v95, v95
	v_add_f32_e32 v152, v93, v152
	v_fma_f32 v104, v99, s87, v109
	v_exp_f32_e32 v104, v104
	v_add_f32_e32 v152, v94, v152
	v_fma_f32 v105, v88, s87, v109
	v_exp_f32_e32 v105, v105
	v_add_f32_e32 v152, v95, v152
	v_fma_f32 v106, v89, s87, v109
	v_exp_f32_e32 v106, v106
	v_add_f32_e32 v152, v104, v152
	v_fma_f32 v107, v90, s87, v109
	v_exp_f32_e32 v107, v107
	v_add_f32_e32 v152, v105, v152
	v_fma_f32 v153, v91, s87, v109
	v_exp_f32_e32 v153, v153
	v_add_f32_e32 v152, v106, v152
	v_fma_f32 v154, v84, s87, v109
	v_exp_f32_e32 v154, v154
	v_add_f32_e32 v152, v107, v152
	v_fma_f32 v155, v85, s87, v109
	v_exp_f32_e32 v155, v155
	v_add_f32_e32 v108, v153, v152
	v_fma_f32 v157, v86, s87, v109
	v_exp_f32_e32 v157, v157
	v_add_f32_e32 v108, v154, v108
	v_fma_f32 v158, v87, s87, v109
	v_exp_f32_e32 v158, v158
	v_add_f32_e32 v108, v155, v108
	v_add_f32_e32 v108, v157, v108
	v_add_f32_e32 v151, v158, v108
	v_fmac_f32_e32 v151, v124, v156
	v_cvt_pk_bf16_f32 v108, v80, v81
	v_cvt_pk_bf16_f32 v109, v83, v92
	v_cvt_pk_bf16_f32 v110, v93, v94
	v_cvt_pk_bf16_f32 v111, v95, v104
	v_cvt_pk_bf16_f32 v152, v105, v106
	v_cvt_pk_bf16_f32 v153, v107, v153
	v_cvt_pk_bf16_f32 v154, v154, v155
	v_cvt_pk_bf16_f32 v155, v157, v158
	v_pk_mul_f32 v[82:83], v[146:147], v[156:157] op_sel_hi:[1,0]
	v_pk_mul_f32 v[80:81], v[144:145], v[156:157] op_sel_hi:[1,0]
	v_pk_mul_f32 v[94:95], v[142:143], v[156:157] op_sel_hi:[1,0]
	v_pk_mul_f32 v[92:93], v[140:141], v[156:157] op_sel_hi:[1,0]
	v_pk_mul_f32 v[106:107], v[138:139], v[156:157] op_sel_hi:[1,0]
	v_pk_mul_f32 v[104:105], v[134:135], v[156:157] op_sel_hi:[1,0]
	v_pk_mul_f32 v[158:159], v[132:133], v[156:157] op_sel_hi:[1,0]
	v_pk_mul_f32 v[156:157], v[128:129], v[156:157] op_sel_hi:[1,0]
	s_waitcnt lgkmcnt(0)
	v_mfma_f32_16x16x32_bf16 v[80:83], v[76:79], v[108:111], v[80:83]
	v_mfma_f32_16x16x32_bf16 v[92:95], v[68:71], v[108:111], v[92:95]
	v_mfma_f32_16x16x32_bf16 v[104:107], v[60:63], v[108:111], v[104:107]
	v_mfma_f32_16x16x32_bf16 v[108:111], v[52:55], v[108:111], v[156:159]
	v_mfma_f32_16x16x32_bf16 v[80:83], v[72:75], v[152:155], v[80:83]
	v_mfma_f32_16x16x32_bf16 v[92:95], v[64:67], v[152:155], v[92:95]
	v_mfma_f32_16x16x32_bf16 v[104:107], v[56:59], v[152:155], v[104:107]
	v_mfma_f32_16x16x32_bf16 v[108:111], v[48:51], v[152:155], v[108:111]
	s_cbranch_execnz .LBB0_609
